# XCD-local seams ph3->4, ph4->5, ph11->12 now active: guard = per-residue XCC-id table (each blockIdx%8 class on exactly one XCC) instead of identity check
# speedup vs baseline: 1.0143x; 1.0143x over previous
; #define LAS __attribute__((address_space(3)))
; __device__ __forceinline__ unsigned xb_add(unsigned* p, unsigned v) { return __hip_atomic_fetch_add(p, v, __ATOMIC_RELAXED, __HIP_MEMORY_SCOPE_AGENT); }
; __device__ __forceinline__ unsigned xb_xcc_id() { return (unsigned)__builtin_amdgcn_s_getreg((3 << 11) | 20) & 0xFu; }
; __device__ __forceinline__ XcdBarrier xcd_barrier_post(unsigned* bar, volatile LAS unsigned* st) {
;     XcdBarrier b; b.bar = bar; b.x = xb_xcc_id(); b.st = st;
;     if (threadIdx.x == 0) (void)xb_add(&bar[XB_XCNT(b.x)], 1u);
;     return b;
_Z10fwd_kernel6Params:
	s_load_dwordx8 s[52:59], s[0:1], 0xb8
	s_add_u32 s8, s0, 0xd0
	v_and_b32_e32 v210, 0x3ff, v0
	s_addc_u32 s9, s1, 0
	v_cmp_gt_u32_e32 vcc, 4, v210
	s_and_saveexec_b64 s[4:5], vcc
	v_lshl_add_u32 v1, v210, 2, 0
	v_add_u32_e32 v1, 0x20000, v1
	v_mov_b32_e32 v2, 0
	ds_write_b32 v1, v2
	s_or_b64 exec, exec, s[4:5]
	s_load_dword s96, s[0:1], 0xd8
	s_waitcnt lgkmcnt(0)
	s_barrier
	s_add_u32 s50, s54, 0x3085c00
	s_getreg_b32 s3, hwreg(HW_REG_XCC_ID, 0, 4)
	s_addc_u32 s51, s55, 0
	s_and_b32 s33, s3, 15
	v_cmp_eq_u32_e64 s[4:5], 0, v210
	s_and_saveexec_b64 s[6:7], s[4:5]
	s_cbranch_execz .LBB0_5
	s_mov_b64 s[10:11], exec
	v_mbcnt_lo_u32_b32 v1, s10, 0
	v_mbcnt_hi_u32_b32 v1, s11, v1
	v_cmp_eq_u32_e32 vcc, 0, v1
	s_and_b64 s[12:13], exec, vcc
	s_mov_b64 exec, s[12:13]
	s_cbranch_execz .LBB0_5
	s_lshl_b32 s3, s33, 8
	s_bcnt1_i32_b64 s10, s[10:11]
	v_mov_b32_e32 v1, s3
	v_mov_b32_e32 v2, s10
	global_atomic_add v1, v2, s[50:51] offset:1024
	s_and_b32 s3, s2, 7
	s_lshl_b32 s3, s3, 2
	s_lshl_b32 s10, 1, s33
	v_mov_b32_e32 v1, s3
	v_mov_b32_e32 v2, s10
	global_atomic_or v1, v2, s[50:51] offset:256

; __device__ __forceinline__ unsigned xb_add(unsigned* p, unsigned v) { return __hip_atomic_fetch_add(p, v, __ATOMIC_RELAXED, __HIP_MEMORY_SCOPE_AGENT); }
; __device__ __forceinline__ void xcd_barrier(const XcdBarrier& b) {
;     asm volatile("s_waitcnt vmcnt(0)" ::: "memory");
;     __syncthreads();
;     if (threadIdx.x == 0) {
;         unsigned* bar = b.bar;
;         __builtin_amdgcn_s_waitcnt(0);
;         unsigned nloc = b.st[0], nx = b.st[1];
;         if (nloc == 0u) { xcd_barrier_complete(bar, b.x, nloc, nx); b.st[0] = nloc; b.st[1] = nx; }
;         const unsigned old = xb_add(&bar[XB_XSUB(b.x)], 1u);
;         const unsigned gen = old / nloc;
;         if (old + 1u == (gen + 1u) * nloc) {
.LBB0_1679:
	s_cmp_lt_i32 s57, 5
	s_cbranch_scc1 .LBB0_1733
	s_waitcnt vmcnt(0)
	s_waitcnt vmcnt(0) lgkmcnt(0)
	s_barrier
	s_and_saveexec_b64 s[6:7], s[4:5]
	s_cbranch_execz .LBB0_1732
	v_mov_b32_e32 v0, 0
	global_load_dwordx4 v[6:9], v0, s[50:51] offset:256 sc1
	global_load_dwordx4 v[10:13], v0, s[50:51] offset:272 sc1
	s_lshl_b32 s3, s33, 8
	s_add_u32 s8, s50, s3
	s_addc_u32 s9, s51, 0
	v_mov_b32_e32 v3, 0x2000
	global_load_dword v4, v3, s[8:9] offset:1024 sc1
	v_mov_b32_e32 v2, 0x20000
	ds_read_b32 v2, v2
	s_waitcnt vmcnt(0) lgkmcnt(0)
	v_add_u32_e32 v14, -1, v6
	v_and_b32_e32 v1, v14, v6
	v_min_u32_e32 v15, v6, v7
	v_add_u32_e32 v14, -1, v7
	v_and_or_b32 v1, v14, v7, v1
	v_min_u32_e32 v15, v15, v8
	v_add_u32_e32 v14, -1, v8
	v_and_or_b32 v1, v14, v8, v1
	v_min_u32_e32 v15, v15, v9
	v_add_u32_e32 v14, -1, v9
	v_and_or_b32 v1, v14, v9, v1
	v_min_u32_e32 v15, v15, v10
	v_add_u32_e32 v14, -1, v10
	v_and_or_b32 v1, v14, v10, v1
	v_min_u32_e32 v15, v15, v11
	v_add_u32_e32 v14, -1, v11
	v_and_or_b32 v1, v14, v11, v1
	v_min_u32_e32 v15, v15, v12
	v_add_u32_e32 v14, -1, v12
	v_and_or_b32 v1, v14, v12, v1
	v_min_u32_e32 v15, v15, v13
	v_add_u32_e32 v14, -1, v13
	v_and_or_b32 v1, v14, v13, v1
	s_nop 0
	v_readfirstlane_b32 s10, v1
	v_readfirstlane_b32 s13, v15
	v_readfirstlane_b32 s11, v4
	v_readfirstlane_b32 s12, v2
	s_nop 1
	s_cmp_lg_u32 s10, 0
	s_cbranch_scc1 .Lseam34_full
	s_cmp_eq_u32 s13, 0
	s_cbranch_scc1 .Lseam34_full
	s_cmpk_lg_i32 s58, 0x100
	s_cbranch_scc1 .Lseam34_full
	s_cmp_eq_u32 s12, 0
	s_cbranch_scc1 .Lseam34_full
	v_mov_b32_e32 v3, 0x1000
	v_mov_b32_e32 v5, 1
	global_atomic_add v3, v3, v5, s[8:9] offset:1024 sc0
	s_waitcnt vmcnt(0)
	v_readfirstlane_b32 s13, v3
	s_add_i32 s14, s11, 1
	s_mul_i32 s14, s14, s12
	s_add_i32 s13, s13, 1
	v_mov_b32_e32 v3, 0x2000
	s_cmp_eq_u32 s13, s14
	s_cbranch_scc1 .Lseam34_lead

; __device__ __forceinline__ unsigned xb_add(unsigned* p, unsigned v) { return __hip_atomic_fetch_add(p, v, __ATOMIC_RELAXED, __HIP_MEMORY_SCOPE_AGENT); }
; __device__ __forceinline__ void xcd_barrier(const XcdBarrier& b) {
;     asm volatile("s_waitcnt vmcnt(0)" ::: "memory");
;     __syncthreads();
;     if (threadIdx.x == 0) {
;         unsigned* bar = b.bar;
;         __builtin_amdgcn_s_waitcnt(0);
;         unsigned nloc = b.st[0], nx = b.st[1];
;         if (nloc == 0u) { xcd_barrier_complete(bar, b.x, nloc, nx); b.st[0] = nloc; b.st[1] = nx; }
;         const unsigned old = xb_add(&bar[XB_XSUB(b.x)], 1u);
;         const unsigned gen = old / nloc;
;         if (old + 1u == (gen + 1u) * nloc) {
.LBB0_1779:
	s_cmp_lt_i32 s57, 6
	s_cbranch_scc1 .LBB0_1833
	s_waitcnt vmcnt(0)
	s_waitcnt vmcnt(0) lgkmcnt(0)
	s_barrier
	s_and_saveexec_b64 s[6:7], s[4:5]
	s_cbranch_execz .LBB0_1832
	v_mov_b32_e32 v0, 0
	global_load_dwordx4 v[6:9], v0, s[50:51] offset:256 sc1
	global_load_dwordx4 v[10:13], v0, s[50:51] offset:272 sc1
	s_lshl_b32 s3, s33, 8
	s_add_u32 s8, s50, s3
	s_addc_u32 s9, s51, 0
	v_mov_b32_e32 v3, 0x2000
	global_load_dword v4, v3, s[8:9] offset:1024 sc1
	v_mov_b32_e32 v2, 0x20000
	ds_read_b32 v2, v2
	s_waitcnt vmcnt(0) lgkmcnt(0)
	v_add_u32_e32 v14, -1, v6
	v_and_b32_e32 v1, v14, v6
	v_min_u32_e32 v15, v6, v7
	v_add_u32_e32 v14, -1, v7
	v_and_or_b32 v1, v14, v7, v1
	v_min_u32_e32 v15, v15, v8
	v_add_u32_e32 v14, -1, v8
	v_and_or_b32 v1, v14, v8, v1
	v_min_u32_e32 v15, v15, v9
	v_add_u32_e32 v14, -1, v9
	v_and_or_b32 v1, v14, v9, v1
	v_min_u32_e32 v15, v15, v10
	v_add_u32_e32 v14, -1, v10
	v_and_or_b32 v1, v14, v10, v1
	v_min_u32_e32 v15, v15, v11
	v_add_u32_e32 v14, -1, v11
	v_and_or_b32 v1, v14, v11, v1
	v_min_u32_e32 v15, v15, v12
	v_add_u32_e32 v14, -1, v12
	v_and_or_b32 v1, v14, v12, v1
	v_min_u32_e32 v15, v15, v13
	v_add_u32_e32 v14, -1, v13
	v_and_or_b32 v1, v14, v13, v1
	s_nop 0
	v_readfirstlane_b32 s10, v1
	v_readfirstlane_b32 s13, v15
	v_readfirstlane_b32 s11, v4
	v_readfirstlane_b32 s12, v2
	s_nop 1
	s_cmp_lg_u32 s10, 0
	s_cbranch_scc1 .Lseam45_full
	s_cmp_eq_u32 s13, 0
	s_cbranch_scc1 .Lseam45_full
	s_cmpk_lg_i32 s58, 0x100
	s_cbranch_scc1 .Lseam45_full
	s_cmp_eq_u32 s12, 0
	s_cbranch_scc1 .Lseam45_full
	v_mov_b32_e32 v3, 0x1000
	v_mov_b32_e32 v5, 1
	global_atomic_add v3, v3, v5, s[8:9] offset:1024 sc0
	s_waitcnt vmcnt(0)
	v_readfirstlane_b32 s13, v3
	s_add_i32 s14, s11, 1
	s_mul_i32 s14, s14, s12
	s_add_i32 s13, s13, 1
	v_mov_b32_e32 v3, 0x2000
	s_cmp_eq_u32 s13, s14
	s_cbranch_scc1 .Lseam45_lead

; __device__ __forceinline__ unsigned xb_add(unsigned* p, unsigned v) { return __hip_atomic_fetch_add(p, v, __ATOMIC_RELAXED, __HIP_MEMORY_SCOPE_AGENT); }
; __device__ __forceinline__ void xcd_barrier(const XcdBarrier& b) {
;     asm volatile("s_waitcnt vmcnt(0)" ::: "memory");
;     __syncthreads();
;     if (threadIdx.x == 0) {
;         unsigned* bar = b.bar;
;         __builtin_amdgcn_s_waitcnt(0);
;         unsigned nloc = b.st[0], nx = b.st[1];
;         if (nloc == 0u) { xcd_barrier_complete(bar, b.x, nloc, nx); b.st[0] = nloc; b.st[1] = nx; }
;         const unsigned old = xb_add(&bar[XB_XSUB(b.x)], 1u);
;         const unsigned gen = old / nloc;
;         if (old + 1u == (gen + 1u) * nloc) {
.LBB0_2546:
	s_cmp_lt_i32 s57, 13
	s_cbranch_scc1 .LBB0_2600
	s_waitcnt vmcnt(0)
	s_waitcnt lgkmcnt(0)
	s_barrier
	s_and_saveexec_b64 s[6:7], s[4:5]
	s_cbranch_execz .LBB0_2599
	v_mov_b32_e32 v0, 0
	global_load_dwordx4 v[6:9], v0, s[50:51] offset:256 sc1
	global_load_dwordx4 v[10:13], v0, s[50:51] offset:272 sc1
	s_lshl_b32 s3, s33, 8
	s_add_u32 s8, s50, s3
	s_addc_u32 s9, s51, 0
	v_mov_b32_e32 v3, 0x2000
	global_load_dword v4, v3, s[8:9] offset:1024 sc1
	v_mov_b32_e32 v2, 0x20000
	ds_read_b32 v2, v2
	s_waitcnt vmcnt(0) lgkmcnt(0)
	v_add_u32_e32 v14, -1, v6
	v_and_b32_e32 v1, v14, v6
	v_min_u32_e32 v15, v6, v7
	v_add_u32_e32 v14, -1, v7
	v_and_or_b32 v1, v14, v7, v1
	v_min_u32_e32 v15, v15, v8
	v_add_u32_e32 v14, -1, v8
	v_and_or_b32 v1, v14, v8, v1
	v_min_u32_e32 v15, v15, v9
	v_add_u32_e32 v14, -1, v9
	v_and_or_b32 v1, v14, v9, v1
	v_min_u32_e32 v15, v15, v10
	v_add_u32_e32 v14, -1, v10
	v_and_or_b32 v1, v14, v10, v1
	v_min_u32_e32 v15, v15, v11
	v_add_u32_e32 v14, -1, v11
	v_and_or_b32 v1, v14, v11, v1
	v_min_u32_e32 v15, v15, v12
	v_add_u32_e32 v14, -1, v12
	v_and_or_b32 v1, v14, v12, v1
	v_min_u32_e32 v15, v15, v13
	v_add_u32_e32 v14, -1, v13
	v_and_or_b32 v1, v14, v13, v1
	s_nop 0
	v_readfirstlane_b32 s10, v1
	v_readfirstlane_b32 s13, v15
	v_readfirstlane_b32 s11, v4
	v_readfirstlane_b32 s12, v2
	s_nop 1
	s_cmp_lg_u32 s10, 0
	s_cbranch_scc1 .Lseam1112_full
	s_cmp_eq_u32 s13, 0
	s_cbranch_scc1 .Lseam1112_full
	s_cmpk_lg_i32 s58, 0x100
	s_cbranch_scc1 .Lseam1112_full
	s_cmp_eq_u32 s12, 0
	s_cbranch_scc1 .Lseam1112_full
	v_mov_b32_e32 v3, 0x1000
	v_mov_b32_e32 v5, 1
	global_atomic_add v3, v3, v5, s[8:9] offset:1024 sc0
	s_waitcnt vmcnt(0)
	v_readfirstlane_b32 s13, v3
	s_add_i32 s14, s11, 1
	s_mul_i32 s14, s14, s12
	s_add_i32 s13, s13, 1
	v_mov_b32_e32 v3, 0x2000
	s_cmp_eq_u32 s13, s14
	s_cbranch_scc1 .Lseam1112_lead
